# hoisted next-tile global loads reordered inside the GEMM compute blocks: each load issued as soon as its address is ready (dependency-preserving) instead of all address VALU first
# speedup vs baseline: 1.0021x; 1.0021x over previous
.LcL_20:
	s_waitcnt lgkmcnt(0)
	s_barrier
	s_setprio 2
	ds_read_b128 v[190:193], v179 offset:36864
	ds_read_b128 v[194:197], v179 offset:41472
	ds_read_b128 v[206:209], v178
	ds_read_b128 v[216:219], v178 offset:4608
	ds_read_b128 v[236:239], v178 offset:9216
	ds_read_b128 v[240:243], v178 offset:13824
	ds_read_b128 v[244:247], v178 offset:32
	s_waitcnt lgkmcnt(4)
	v_mfma_f32_32x32x16_bf16 v[114:129], v[190:193], v[206:209], v[114:129]
	s_ashr_i32 s1, s0, 31
	s_lshl_b64 s[6:7], s[0:1], 7
	v_lshl_add_u64 v[154:155], v[180:181], 0, s[6:7]
	v_mfma_f32_32x32x16_bf16 v[98:113], v[194:197], v[206:209], v[98:113]
	global_load_dwordx4 v[142:145], v[154:155], off
	s_nop 0
	v_add_co_u32_e32 v130, vcc, 0x2c000, v154
	ds_read_b128 v[206:209], v178 offset:4640
	ds_read_b128 v[198:201], v179 offset:36896
	ds_read_b128 v[202:205], v179 offset:41504
	s_waitcnt lgkmcnt(6)
	v_mfma_f32_32x32x16_bf16 v[82:97], v[190:193], v[216:219], v[82:97]
	v_addc_co_u32_e32 v131, vcc, 0, v155, vcc
	global_load_dwordx4 v[130:133], v[130:131], off
	v_add_co_u32_e32 v134, vcc, 0x58000, v154
	v_mfma_f32_32x32x16_bf16 v[66:81], v[194:197], v[216:219], v[66:81]
	v_addc_co_u32_e32 v135, vcc, 0, v155, vcc
	global_load_dwordx4 v[134:137], v[134:135], off
	s_nop 0
	ds_read_b128 v[216:219], v178 offset:9248
	s_waitcnt lgkmcnt(6)
	v_mfma_f32_32x32x16_bf16 v[50:65], v[190:193], v[236:239], v[50:65]
	v_add_co_u32_e32 v138, vcc, 0x84000, v154
	v_addc_co_u32_e32 v139, vcc, 0, v155, vcc
	global_load_dwordx4 v[138:141], v[138:139], off
	v_mfma_f32_32x32x16_bf16 v[34:49], v[194:197], v[236:239], v[34:49]
	v_add_co_u32_e32 v146, vcc, 0xb0000, v154
	v_addc_co_u32_e32 v147, vcc, 0, v155, vcc
	global_load_dwordx4 v[146:149], v[146:147], off
	ds_read_b128 v[236:239], v178 offset:13856
	s_waitcnt lgkmcnt(6)
	v_mfma_f32_32x32x16_bf16 v[18:33], v[190:193], v[240:243], v[18:33]
	s_nop 0
	v_add_co_u32_e32 v150, vcc, 0xdc000, v154
	s_nop 0
	v_mfma_f32_32x32x16_bf16 v[2:17], v[194:197], v[240:243], v[2:17]
	v_addc_co_u32_e32 v151, vcc, 0, v155, vcc
	global_load_dwordx4 v[150:153], v[150:151], off
	v_add_co_u32_e32 v156, vcc, 0x108000, v154
	ds_read_b128 v[240:243], v178 offset:64
	s_waitcnt lgkmcnt(3)
	v_mfma_f32_32x32x16_bf16 v[114:129], v[198:201], v[244:247], v[114:129]
	v_addc_co_u32_e32 v157, vcc, 0, v155, vcc
	v_add_co_u32_e32 v158, vcc, 0x134000, v154
	s_nop 1
	v_mfma_f32_32x32x16_bf16 v[98:113], v[202:205], v[244:247], v[98:113]
	v_addc_co_u32_e32 v159, vcc, 0, v155, vcc
	global_load_dwordx4 v[154:157], v[156:157], off
	s_nop 0
	ds_read_b128 v[244:247], v178 offset:4672
	ds_read_b128 v[190:193], v179 offset:36928
	ds_read_b128 v[194:197], v179 offset:41536
	v_mfma_f32_32x32x16_bf16 v[82:97], v[198:201], v[206:209], v[82:97]
	global_load_dwordx4 v[158:161], v[158:159], off
	v_lshl_add_u64 v[170:171], v[182:183], 0, s[6:7]
	s_nop 0
	v_mfma_f32_32x32x16_bf16 v[66:81], v[202:205], v[206:209], v[66:81]
	global_load_dwordx4 v[162:165], v[170:171], off
	s_nop 0
	v_add_co_u32_e32 v166, vcc, 0x2c000, v170
	ds_read_b128 v[206:209], v178 offset:9280
	s_waitcnt lgkmcnt(6)
	v_mfma_f32_32x32x16_bf16 v[50:65], v[198:201], v[216:219], v[50:65]
	v_addc_co_u32_e32 v167, vcc, 0, v171, vcc
	global_load_dwordx4 v[166:169], v[166:167], off
	v_add_co_u32_e32 v172, vcc, 0x58000, v170
	v_mfma_f32_32x32x16_bf16 v[34:49], v[202:205], v[216:219], v[34:49]
	v_addc_co_u32_e32 v173, vcc, 0, v171, vcc
	v_add_co_u32_e32 v174, vcc, 0x84000, v170
	s_nop 1
	ds_read_b128 v[216:219], v178 offset:13888
	s_waitcnt lgkmcnt(6)
	v_mfma_f32_32x32x16_bf16 v[18:33], v[198:201], v[236:239], v[18:33]
	v_addc_co_u32_e32 v175, vcc, 0, v171, vcc
	global_load_dwordx4 v[170:173], v[172:173], off
	s_nop 0
	v_mfma_f32_32x32x16_bf16 v[2:17], v[202:205], v[236:239], v[2:17]
	global_load_dwordx4 v[174:177], v[174:175], off
	s_add_i32 s0, s0, 1
	s_nop 0
	ds_read_b128 v[236:239], v178 offset:96
	s_waitcnt lgkmcnt(3)
	v_mfma_f32_32x32x16_bf16 v[114:129], v[190:193], v[240:243], v[114:129]
	s_cmp_lg_u32 s0, 44
	v_mfma_f32_32x32x16_bf16 v[98:113], v[194:197], v[240:243], v[98:113]
	ds_read_b128 v[240:243], v178 offset:4704
	ds_read_b128 v[198:201], v179 offset:36960
	ds_read_b128 v[202:205], v179 offset:41568
	v_mfma_f32_32x32x16_bf16 v[82:97], v[190:193], v[244:247], v[82:97]
	v_mfma_f32_32x32x16_bf16 v[66:81], v[194:197], v[244:247], v[66:81]
	ds_read_b128 v[244:247], v178 offset:9312
	s_waitcnt lgkmcnt(6)
	v_mfma_f32_32x32x16_bf16 v[50:65], v[190:193], v[206:209], v[50:65]
	v_mfma_f32_32x32x16_bf16 v[34:49], v[194:197], v[206:209], v[34:49]
	ds_read_b128 v[206:209], v178 offset:13920
	s_waitcnt lgkmcnt(6)
	v_mfma_f32_32x32x16_bf16 v[18:33], v[190:193], v[216:219], v[18:33]
	v_mfma_f32_32x32x16_bf16 v[2:17], v[194:197], v[216:219], v[2:17]
	s_waitcnt lgkmcnt(2)
	v_mfma_f32_32x32x16_bf16 v[114:129], v[198:201], v[236:239], v[114:129]
	v_mfma_f32_32x32x16_bf16 v[98:113], v[202:205], v[236:239], v[98:113]
	v_mfma_f32_32x32x16_bf16 v[82:97], v[198:201], v[240:243], v[82:97]
	v_mfma_f32_32x32x16_bf16 v[66:81], v[202:205], v[240:243], v[66:81]
	s_waitcnt lgkmcnt(1)
	v_mfma_f32_32x32x16_bf16 v[50:65], v[198:201], v[244:247], v[50:65]
	v_mfma_f32_32x32x16_bf16 v[34:49], v[202:205], v[244:247], v[34:49]
	s_waitcnt lgkmcnt(0)
	v_mfma_f32_32x32x16_bf16 v[18:33], v[198:201], v[206:209], v[18:33]
	v_mfma_f32_32x32x16_bf16 v[2:17], v[202:205], v[206:209], v[2:17]
	s_setprio 0
	s_cbranch_scc1 .Ltail_20
	s_add_i32 s2, s2, 1
	s_cmp_ge_i32 s2, s4
	s_cbranch_scc1 .Lz_20
	s_mul_i32 s0, s2, s82
	s_add_i32 s0, s0, s63
	s_ashr_i32 s1, s0, 31
	s_lshr_b32 s1, s1, 28
	s_add_i32 s1, s0, s1
	s_ashr_i32 s6, s1, 4
	s_and_b32 s1, s1, -16
	s_sub_i32 s0, s0, s1
	s_lshl_b32 s1, s6, 1
	s_and_b32 s6, s0, 1
	s_or_b32 s6, s6, s1
	s_lshr_b32 s7, s0, 1
	v_readlane_b32 s0, v252, 35
	s_sub_i32 s8, 0x7f, s6
	v_readlane_b32 s1, v252, 36
	s_and_b64 s[0:1], s[0:1], exec
	s_mul_i32 s0, s7, 0x58000
	s_cselect_b32 s6, s8, s6
	s_ashr_i32 s1, s0, 31
	v_mov_b32_e32 v0, 0x160000
	v_mad_i64_i32 v[180:181], s[6:7], s6, v0, v[186:187]
	v_lshl_add_u64 v[182:183], s[0:1], 1, v[188:189]

.LcL_34:
	s_waitcnt lgkmcnt(0)
	s_barrier
	s_setprio 2
	ds_read_b128 v[190:193], v179 offset:36864
	ds_read_b128 v[194:197], v179 offset:41472
	ds_read_b128 v[206:209], v178
	ds_read_b128 v[216:219], v178 offset:4608
	ds_read_b128 v[236:239], v178 offset:9216
	ds_read_b128 v[240:243], v178 offset:13824
	ds_read_b128 v[244:247], v178 offset:32
	s_waitcnt lgkmcnt(4)
	v_mfma_f32_32x32x16_bf16 v[114:129], v[190:193], v[206:209], v[114:129]
	s_ashr_i32 s1, s0, 31
	s_lshl_b64 s[6:7], s[0:1], 7
	v_lshl_add_u64 v[154:155], v[180:181], 0, s[6:7]
	v_mfma_f32_32x32x16_bf16 v[98:113], v[194:197], v[206:209], v[98:113]
	global_load_dwordx4 v[142:145], v[154:155], off
	s_nop 0
	v_add_co_u32_e32 v130, vcc, 0x10000, v154
	ds_read_b128 v[206:209], v178 offset:4640
	ds_read_b128 v[198:201], v179 offset:36896
	ds_read_b128 v[202:205], v179 offset:41504
	s_waitcnt lgkmcnt(6)
	v_mfma_f32_32x32x16_bf16 v[82:97], v[190:193], v[216:219], v[82:97]
	v_addc_co_u32_e32 v131, vcc, 0, v155, vcc
	global_load_dwordx4 v[130:133], v[130:131], off
	v_add_co_u32_e32 v134, vcc, 0x20000, v154
	v_mfma_f32_32x32x16_bf16 v[66:81], v[194:197], v[216:219], v[66:81]
	v_addc_co_u32_e32 v135, vcc, 0, v155, vcc
	global_load_dwordx4 v[134:137], v[134:135], off
	s_nop 0
	ds_read_b128 v[216:219], v178 offset:9248
	s_waitcnt lgkmcnt(6)
	v_mfma_f32_32x32x16_bf16 v[50:65], v[190:193], v[236:239], v[50:65]
	v_add_co_u32_e32 v138, vcc, 0x30000, v154
	v_addc_co_u32_e32 v139, vcc, 0, v155, vcc
	global_load_dwordx4 v[138:141], v[138:139], off
	v_mfma_f32_32x32x16_bf16 v[34:49], v[194:197], v[236:239], v[34:49]
	v_add_co_u32_e32 v146, vcc, 0x40000, v154
	v_addc_co_u32_e32 v147, vcc, 0, v155, vcc
	global_load_dwordx4 v[146:149], v[146:147], off
	ds_read_b128 v[236:239], v178 offset:13856
	s_waitcnt lgkmcnt(6)
	v_mfma_f32_32x32x16_bf16 v[18:33], v[190:193], v[240:243], v[18:33]
	s_nop 0
	v_add_co_u32_e32 v150, vcc, 0x50000, v154
	s_nop 0
	v_mfma_f32_32x32x16_bf16 v[2:17], v[194:197], v[240:243], v[2:17]
	v_addc_co_u32_e32 v151, vcc, 0, v155, vcc
	global_load_dwordx4 v[150:153], v[150:151], off
	v_add_co_u32_e32 v156, vcc, 0x60000, v154
	ds_read_b128 v[240:243], v178 offset:64
	s_waitcnt lgkmcnt(3)
	v_mfma_f32_32x32x16_bf16 v[114:129], v[198:201], v[244:247], v[114:129]
	v_addc_co_u32_e32 v157, vcc, 0, v155, vcc
	v_add_co_u32_e32 v158, vcc, 0x70000, v154
	s_nop 1
	v_mfma_f32_32x32x16_bf16 v[98:113], v[202:205], v[244:247], v[98:113]
	v_addc_co_u32_e32 v159, vcc, 0, v155, vcc
	global_load_dwordx4 v[154:157], v[156:157], off
	s_nop 0
	ds_read_b128 v[244:247], v178 offset:4672
	ds_read_b128 v[190:193], v179 offset:36928
	ds_read_b128 v[194:197], v179 offset:41536
	v_mfma_f32_32x32x16_bf16 v[82:97], v[198:201], v[206:209], v[82:97]
	global_load_dwordx4 v[158:161], v[158:159], off
	v_lshl_add_u64 v[170:171], v[182:183], 0, s[6:7]
	s_nop 0
	v_mfma_f32_32x32x16_bf16 v[66:81], v[202:205], v[206:209], v[66:81]
	global_load_dwordx4 v[162:165], v[170:171], off
	s_nop 0
	v_add_co_u32_e32 v166, vcc, 0x10000, v170
	ds_read_b128 v[206:209], v178 offset:9280
	s_waitcnt lgkmcnt(6)
	v_mfma_f32_32x32x16_bf16 v[50:65], v[198:201], v[216:219], v[50:65]
	v_addc_co_u32_e32 v167, vcc, 0, v171, vcc
	global_load_dwordx4 v[166:169], v[166:167], off
	v_add_co_u32_e32 v172, vcc, 0x20000, v170
	v_mfma_f32_32x32x16_bf16 v[34:49], v[202:205], v[216:219], v[34:49]
	v_addc_co_u32_e32 v173, vcc, 0, v171, vcc
	v_add_co_u32_e32 v174, vcc, 0x30000, v170
	s_nop 1
	ds_read_b128 v[216:219], v178 offset:13888
	s_waitcnt lgkmcnt(6)
	v_mfma_f32_32x32x16_bf16 v[18:33], v[198:201], v[236:239], v[18:33]
	v_addc_co_u32_e32 v175, vcc, 0, v171, vcc
	global_load_dwordx4 v[170:173], v[172:173], off
	s_nop 0
	v_mfma_f32_32x32x16_bf16 v[2:17], v[202:205], v[236:239], v[2:17]
	global_load_dwordx4 v[174:177], v[174:175], off
	s_add_i32 s0, s0, 1
	s_nop 0
	ds_read_b128 v[236:239], v178 offset:96
	s_waitcnt lgkmcnt(3)
	v_mfma_f32_32x32x16_bf16 v[114:129], v[190:193], v[240:243], v[114:129]
	s_cmp_lg_u32 s0, 16
	v_mfma_f32_32x32x16_bf16 v[98:113], v[194:197], v[240:243], v[98:113]
	ds_read_b128 v[240:243], v178 offset:4704
	ds_read_b128 v[198:201], v179 offset:36960
	ds_read_b128 v[202:205], v179 offset:41568
	v_mfma_f32_32x32x16_bf16 v[82:97], v[190:193], v[244:247], v[82:97]
	v_mfma_f32_32x32x16_bf16 v[66:81], v[194:197], v[244:247], v[66:81]
	ds_read_b128 v[244:247], v178 offset:9312
	s_waitcnt lgkmcnt(6)
	v_mfma_f32_32x32x16_bf16 v[50:65], v[190:193], v[206:209], v[50:65]
	v_mfma_f32_32x32x16_bf16 v[34:49], v[194:197], v[206:209], v[34:49]
	ds_read_b128 v[206:209], v178 offset:13920
	s_waitcnt lgkmcnt(6)
	v_mfma_f32_32x32x16_bf16 v[18:33], v[190:193], v[216:219], v[18:33]
	v_mfma_f32_32x32x16_bf16 v[2:17], v[194:197], v[216:219], v[2:17]
	s_waitcnt lgkmcnt(2)
	v_mfma_f32_32x32x16_bf16 v[114:129], v[198:201], v[236:239], v[114:129]
	v_mfma_f32_32x32x16_bf16 v[98:113], v[202:205], v[236:239], v[98:113]
	v_mfma_f32_32x32x16_bf16 v[82:97], v[198:201], v[240:243], v[82:97]
	v_mfma_f32_32x32x16_bf16 v[66:81], v[202:205], v[240:243], v[66:81]
	s_waitcnt lgkmcnt(1)
	v_mfma_f32_32x32x16_bf16 v[50:65], v[198:201], v[244:247], v[50:65]
	v_mfma_f32_32x32x16_bf16 v[34:49], v[202:205], v[244:247], v[34:49]
	s_waitcnt lgkmcnt(0)
	v_mfma_f32_32x32x16_bf16 v[18:33], v[198:201], v[206:209], v[18:33]
	v_mfma_f32_32x32x16_bf16 v[2:17], v[202:205], v[206:209], v[2:17]
	s_setprio 0
	s_cbranch_scc1 .Ltail_34
	s_add_i32 s2, s2, 1
	s_cmp_ge_i32 s2, s4
	s_cbranch_scc1 .Lz_34
	s_mul_i32 s0, s2, s82
	s_add_i32 s0, s0, s63
	s_mul_hi_i32 s1, s0, 0x2e8ba2e9
	s_lshr_b32 s6, s1, 31
	s_ashr_i32 s1, s1, 4
	s_add_i32 s1, s1, s6
	s_mul_i32 s6, s1, 0x58
	s_sub_i32 s0, s0, s6
	s_lshl_b32 s1, s1, 1
	s_and_b32 s6, s0, 1
	s_or_b32 s1, s6, s1
	v_readlane_b32 s6, v252, 35
	s_ashr_i32 s0, s0, 1
	s_sub_i32 s8, 0x7f, s1
	v_readlane_b32 s7, v252, 36
	s_and_b64 s[6:7], s[6:7], exec
	s_cselect_b32 s6, s8, s1
	s_ashr_i32 s7, s6, 31
	s_ashr_i32 s1, s0, 31
	s_lshl_b64 s[6:7], s[6:7], 19
	s_lshl_b64 s[0:1], s[0:1], 18
	v_lshl_add_u64 v[180:181], v[186:187], 0, s[6:7]
	v_lshl_add_u64 v[182:183], v[188:189], 0, s[0:1]

.LcL_62:
	s_waitcnt lgkmcnt(0)
	s_barrier
	s_setprio 2
	ds_read_b128 v[190:193], v179 offset:36864
	ds_read_b128 v[194:197], v179 offset:41472
	ds_read_b128 v[206:209], v178
	ds_read_b128 v[216:219], v178 offset:4608
	ds_read_b128 v[236:239], v178 offset:9216
	ds_read_b128 v[240:243], v178 offset:13824
	ds_read_b128 v[244:247], v178 offset:32
	s_waitcnt lgkmcnt(4)
	v_mfma_f32_32x32x16_bf16 v[114:129], v[190:193], v[206:209], v[114:129]
	s_ashr_i32 s1, s0, 31
	s_lshl_b64 s[4:5], s[0:1], 7
	v_lshl_add_u64 v[154:155], v[180:181], 0, s[4:5]
	v_mfma_f32_32x32x16_bf16 v[98:113], v[194:197], v[206:209], v[98:113]
	global_load_dwordx4 v[142:145], v[154:155], off
	s_nop 0
	v_add_co_u32_e32 v130, vcc, 0x10000, v154
	ds_read_b128 v[206:209], v178 offset:4640
	ds_read_b128 v[198:201], v179 offset:36896
	ds_read_b128 v[202:205], v179 offset:41504
	s_waitcnt lgkmcnt(6)
	v_mfma_f32_32x32x16_bf16 v[82:97], v[190:193], v[216:219], v[82:97]
	v_addc_co_u32_e32 v131, vcc, 0, v155, vcc
	global_load_dwordx4 v[130:133], v[130:131], off
	v_add_co_u32_e32 v134, vcc, 0x20000, v154
	v_mfma_f32_32x32x16_bf16 v[66:81], v[194:197], v[216:219], v[66:81]
	v_addc_co_u32_e32 v135, vcc, 0, v155, vcc
	global_load_dwordx4 v[134:137], v[134:135], off
	s_nop 0
	ds_read_b128 v[216:219], v178 offset:9248
	s_waitcnt lgkmcnt(6)
	v_mfma_f32_32x32x16_bf16 v[50:65], v[190:193], v[236:239], v[50:65]
	v_add_co_u32_e32 v138, vcc, 0x30000, v154
	v_addc_co_u32_e32 v139, vcc, 0, v155, vcc
	global_load_dwordx4 v[138:141], v[138:139], off
	v_mfma_f32_32x32x16_bf16 v[34:49], v[194:197], v[236:239], v[34:49]
	v_add_co_u32_e32 v146, vcc, 0x40000, v154
	v_addc_co_u32_e32 v147, vcc, 0, v155, vcc
	global_load_dwordx4 v[146:149], v[146:147], off
	ds_read_b128 v[236:239], v178 offset:13856
	s_waitcnt lgkmcnt(6)
	v_mfma_f32_32x32x16_bf16 v[18:33], v[190:193], v[240:243], v[18:33]
	s_nop 0
	v_add_co_u32_e32 v150, vcc, 0x50000, v154
	s_nop 0
	v_mfma_f32_32x32x16_bf16 v[2:17], v[194:197], v[240:243], v[2:17]
	v_addc_co_u32_e32 v151, vcc, 0, v155, vcc
	global_load_dwordx4 v[150:153], v[150:151], off
	v_add_co_u32_e32 v156, vcc, 0x60000, v154
	ds_read_b128 v[240:243], v178 offset:64
	s_waitcnt lgkmcnt(3)
	v_mfma_f32_32x32x16_bf16 v[114:129], v[198:201], v[244:247], v[114:129]
	v_addc_co_u32_e32 v157, vcc, 0, v155, vcc
	v_add_co_u32_e32 v158, vcc, 0x70000, v154
	s_nop 1
	v_mfma_f32_32x32x16_bf16 v[98:113], v[202:205], v[244:247], v[98:113]
	v_addc_co_u32_e32 v159, vcc, 0, v155, vcc
	global_load_dwordx4 v[154:157], v[156:157], off
	s_nop 0
	ds_read_b128 v[244:247], v178 offset:4672
	ds_read_b128 v[190:193], v179 offset:36928
	ds_read_b128 v[194:197], v179 offset:41536
	v_mfma_f32_32x32x16_bf16 v[82:97], v[198:201], v[206:209], v[82:97]
	global_load_dwordx4 v[158:161], v[158:159], off
	v_lshl_add_u64 v[170:171], v[182:183], 0, s[4:5]
	s_nop 0
	v_mfma_f32_32x32x16_bf16 v[66:81], v[202:205], v[206:209], v[66:81]
	global_load_dwordx4 v[162:165], v[170:171], off
	s_nop 0
	v_add_co_u32_e32 v166, vcc, 0x10000, v170
	ds_read_b128 v[206:209], v178 offset:9280
	s_waitcnt lgkmcnt(6)
	v_mfma_f32_32x32x16_bf16 v[50:65], v[198:201], v[216:219], v[50:65]
	v_addc_co_u32_e32 v167, vcc, 0, v171, vcc
	global_load_dwordx4 v[166:169], v[166:167], off
	v_add_co_u32_e32 v172, vcc, 0x20000, v170
	v_mfma_f32_32x32x16_bf16 v[34:49], v[202:205], v[216:219], v[34:49]
	v_addc_co_u32_e32 v173, vcc, 0, v171, vcc
	v_add_co_u32_e32 v174, vcc, 0x30000, v170
	s_nop 1
	ds_read_b128 v[216:219], v178 offset:13888
	s_waitcnt lgkmcnt(6)
	v_mfma_f32_32x32x16_bf16 v[18:33], v[198:201], v[236:239], v[18:33]
	v_addc_co_u32_e32 v175, vcc, 0, v171, vcc
	global_load_dwordx4 v[170:173], v[172:173], off
	s_nop 0
	v_mfma_f32_32x32x16_bf16 v[2:17], v[202:205], v[236:239], v[2:17]
	global_load_dwordx4 v[174:177], v[174:175], off
	s_add_i32 s0, s0, 1
	s_nop 0
	ds_read_b128 v[236:239], v178 offset:96
	s_waitcnt lgkmcnt(3)
	v_mfma_f32_32x32x16_bf16 v[114:129], v[190:193], v[240:243], v[114:129]
	s_cmp_lg_u32 s0, 16
	v_mfma_f32_32x32x16_bf16 v[98:113], v[194:197], v[240:243], v[98:113]
	ds_read_b128 v[240:243], v178 offset:4704
	ds_read_b128 v[198:201], v179 offset:36960
	ds_read_b128 v[202:205], v179 offset:41568
	v_mfma_f32_32x32x16_bf16 v[82:97], v[190:193], v[244:247], v[82:97]
	v_mfma_f32_32x32x16_bf16 v[66:81], v[194:197], v[244:247], v[66:81]
	ds_read_b128 v[244:247], v178 offset:9312
	s_waitcnt lgkmcnt(6)
	v_mfma_f32_32x32x16_bf16 v[50:65], v[190:193], v[206:209], v[50:65]
	v_mfma_f32_32x32x16_bf16 v[34:49], v[194:197], v[206:209], v[34:49]
	ds_read_b128 v[206:209], v178 offset:13920
	s_waitcnt lgkmcnt(6)
	v_mfma_f32_32x32x16_bf16 v[18:33], v[190:193], v[216:219], v[18:33]
	v_mfma_f32_32x32x16_bf16 v[2:17], v[194:197], v[216:219], v[2:17]
	s_waitcnt lgkmcnt(2)
	v_mfma_f32_32x32x16_bf16 v[114:129], v[198:201], v[236:239], v[114:129]
	v_mfma_f32_32x32x16_bf16 v[98:113], v[202:205], v[236:239], v[98:113]
	v_mfma_f32_32x32x16_bf16 v[82:97], v[198:201], v[240:243], v[82:97]
	v_mfma_f32_32x32x16_bf16 v[66:81], v[202:205], v[240:243], v[66:81]
	s_waitcnt lgkmcnt(1)
	v_mfma_f32_32x32x16_bf16 v[50:65], v[198:201], v[244:247], v[50:65]
	v_mfma_f32_32x32x16_bf16 v[34:49], v[202:205], v[244:247], v[34:49]
	s_waitcnt lgkmcnt(0)
	v_mfma_f32_32x32x16_bf16 v[18:33], v[198:201], v[206:209], v[18:33]
	v_mfma_f32_32x32x16_bf16 v[2:17], v[202:205], v[206:209], v[2:17]
	s_setprio 0
	s_cbranch_scc1 .Ltail_62
	s_add_i32 s2, s2, 1
	s_cmp_ge_i32 s2, s6
	s_cbranch_scc1 .Lz_62
	s_mul_i32 s0, s2, s82
	s_add_i32 s0, s0, s63
	s_ashr_i32 s1, s0, 31
	s_lshr_b32 s1, s1, 28
	s_add_i32 s1, s0, s1
	s_ashr_i32 s4, s1, 4
	s_and_b32 s1, s1, -16
	s_sub_i32 s0, s0, s1
	s_lshl_b32 s1, s4, 1
	s_and_b32 s4, s0, 1
	s_or_b32 s1, s4, s1
	v_readlane_b32 s4, v252, 35
	s_ashr_i32 s0, s0, 1
	s_sub_i32 s8, 0x7f, s1
	v_readlane_b32 s5, v252, 36
	s_and_b64 s[4:5], s[4:5], exec
	s_cselect_b32 s4, s8, s1
	s_ashr_i32 s5, s4, 31
	s_ashr_i32 s1, s0, 31
	s_lshl_b64 s[4:5], s[4:5], 19
	s_lshl_b64 s[0:1], s[0:1], 18
	v_lshl_add_u64 v[180:181], v[186:187], 0, s[4:5]
	v_lshl_add_u64 v[182:183], v[188:189], 0, s[0:1]

.LcL_92:
	s_waitcnt lgkmcnt(0)
	s_barrier
	s_setprio 2
	ds_read_b128 v[190:193], v181 offset:36864
	ds_read_b128 v[194:197], v181 offset:41472
	ds_read_b128 v[206:209], v180
	ds_read_b128 v[216:219], v180 offset:4608
	ds_read_b128 v[236:239], v180 offset:9216
	ds_read_b128 v[240:243], v180 offset:13824
	ds_read_b128 v[244:247], v180 offset:32
	s_waitcnt lgkmcnt(4)
	v_mfma_f32_32x32x16_bf16 v[114:129], v[190:193], v[206:209], v[114:129]
	s_ashr_i32 s9, s8, 31
	s_lshl_b64 s[12:13], s[10:11], 6
	s_lshl_b64 s[4:5], s[8:9], 7
	v_mfma_f32_32x32x16_bf16 v[98:113], v[194:197], v[206:209], v[98:113]
	v_lshl_add_u64 v[130:131], v[186:187], 0, s[4:5]
	global_load_dwordx4 v[130:133], v[130:131], off
	s_nop 0
	ds_read_b128 v[206:209], v180 offset:4640
	ds_read_b128 v[198:201], v181 offset:36896
	ds_read_b128 v[202:205], v181 offset:41504
	s_waitcnt lgkmcnt(6)
	v_mfma_f32_32x32x16_bf16 v[82:97], v[190:193], v[216:219], v[82:97]
	v_lshl_add_u64 v[138:139], v[186:187], 0, s[12:13]
	v_lshl_add_u64 v[134:135], v[138:139], 0, s[4:5]
	global_load_dwordx4 v[134:137], v[134:135], off
	v_mfma_f32_32x32x16_bf16 v[66:81], v[194:197], v[216:219], v[66:81]
	s_nop 0
	v_lshl_add_u64 v[138:139], v[138:139], 0, s[12:13]
	v_lshl_add_u64 v[146:147], v[138:139], 0, s[12:13]
	ds_read_b128 v[216:219], v180 offset:9248
	s_waitcnt lgkmcnt(6)
	v_mfma_f32_32x32x16_bf16 v[50:65], v[190:193], v[236:239], v[50:65]
	v_lshl_add_u64 v[140:141], v[138:139], 0, s[4:5]
	global_load_dwordx4 v[138:141], v[140:141], off
	s_nop 0
	v_mfma_f32_32x32x16_bf16 v[34:49], v[194:197], v[236:239], v[34:49]
	v_lshl_add_u64 v[142:143], v[146:147], 0, s[4:5]
	global_load_dwordx4 v[142:145], v[142:143], off
	s_nop 0
	ds_read_b128 v[236:239], v180 offset:13856
	s_waitcnt lgkmcnt(6)
	v_mfma_f32_32x32x16_bf16 v[18:33], v[190:193], v[240:243], v[18:33]
	v_lshl_add_u64 v[146:147], v[146:147], 0, s[12:13]
	v_lshl_add_u64 v[154:155], v[146:147], 0, s[12:13]
	v_lshl_add_u64 v[148:149], v[146:147], 0, s[4:5]
	v_mfma_f32_32x32x16_bf16 v[2:17], v[194:197], v[240:243], v[2:17]
	global_load_dwordx4 v[146:149], v[148:149], off
	s_nop 0
	v_lshl_add_u64 v[150:151], v[154:155], 0, s[4:5]
	ds_read_b128 v[240:243], v180 offset:64
	s_waitcnt lgkmcnt(3)
	v_mfma_f32_32x32x16_bf16 v[114:129], v[198:201], v[244:247], v[114:129]
	global_load_dwordx4 v[150:153], v[150:151], off
	s_nop 0
	v_lshl_add_u64 v[154:155], v[154:155], 0, s[12:13]
	v_mfma_f32_32x32x16_bf16 v[98:113], v[202:205], v[244:247], v[98:113]
	v_lshl_add_u64 v[156:157], v[154:155], 0, s[4:5]
	v_lshl_add_u64 v[154:155], v[154:155], 0, s[12:13]
	v_lshl_add_u64 v[158:159], v[154:155], 0, s[4:5]
	ds_read_b128 v[244:247], v180 offset:4672
	ds_read_b128 v[190:193], v181 offset:36928
	ds_read_b128 v[194:197], v181 offset:41536
	v_mfma_f32_32x32x16_bf16 v[82:97], v[198:201], v[206:209], v[82:97]
	global_load_dwordx4 v[154:157], v[156:157], off
	s_nop 0
	global_load_dwordx4 v[158:161], v[158:159], off
	v_mfma_f32_32x32x16_bf16 v[66:81], v[202:205], v[206:209], v[66:81]
	s_nop 0
	v_lshl_add_u64 v[162:163], v[188:189], 0, s[4:5]
	global_load_dwordx4 v[162:165], v[162:163], off
	ds_read_b128 v[206:209], v180 offset:9280
	s_waitcnt lgkmcnt(6)
	v_mfma_f32_32x32x16_bf16 v[50:65], v[198:201], v[216:219], v[50:65]
	s_nop 0
	s_lshl_b64 s[12:13], s[10:11], 6
	v_lshl_add_u64 v[170:171], v[188:189], 0, s[12:13]
	v_mfma_f32_32x32x16_bf16 v[34:49], v[202:205], v[216:219], v[34:49]
	v_lshl_add_u64 v[166:167], v[170:171], 0, s[4:5]
	global_load_dwordx4 v[166:169], v[166:167], off
	s_nop 0
	ds_read_b128 v[216:219], v180 offset:13888
	s_waitcnt lgkmcnt(6)
	v_mfma_f32_32x32x16_bf16 v[18:33], v[198:201], v[236:239], v[18:33]
	v_lshl_add_u64 v[170:171], v[170:171], 0, s[12:13]
	v_lshl_add_u64 v[172:173], v[170:171], 0, s[4:5]
	v_lshl_add_u64 v[170:171], v[170:171], 0, s[12:13]
	v_mfma_f32_32x32x16_bf16 v[2:17], v[202:205], v[236:239], v[2:17]
	v_lshl_add_u64 v[174:175], v[170:171], 0, s[4:5]
	global_load_dwordx4 v[170:173], v[172:173], off
	s_nop 0
	ds_read_b128 v[236:239], v180 offset:96
	s_waitcnt lgkmcnt(3)
	v_mfma_f32_32x32x16_bf16 v[114:129], v[190:193], v[240:243], v[114:129]
	global_load_dwordx4 v[174:177], v[174:175], off
	s_add_i32 s8, s8, 1
	s_cmp_lg_u32 s8, s19
	v_mfma_f32_32x32x16_bf16 v[98:113], v[194:197], v[240:243], v[98:113]
	ds_read_b128 v[240:243], v180 offset:4704
	ds_read_b128 v[198:201], v181 offset:36960
	ds_read_b128 v[202:205], v181 offset:41568
	v_mfma_f32_32x32x16_bf16 v[82:97], v[190:193], v[244:247], v[82:97]
	v_mfma_f32_32x32x16_bf16 v[66:81], v[194:197], v[244:247], v[66:81]
	ds_read_b128 v[244:247], v180 offset:9312
	s_waitcnt lgkmcnt(6)
	v_mfma_f32_32x32x16_bf16 v[50:65], v[190:193], v[206:209], v[50:65]
	v_mfma_f32_32x32x16_bf16 v[34:49], v[194:197], v[206:209], v[34:49]
	ds_read_b128 v[206:209], v180 offset:13920
	s_waitcnt lgkmcnt(6)
	v_mfma_f32_32x32x16_bf16 v[18:33], v[190:193], v[216:219], v[18:33]
	v_mfma_f32_32x32x16_bf16 v[2:17], v[194:197], v[216:219], v[2:17]
	s_waitcnt lgkmcnt(2)
	v_mfma_f32_32x32x16_bf16 v[114:129], v[198:201], v[236:239], v[114:129]
	v_mfma_f32_32x32x16_bf16 v[98:113], v[202:205], v[236:239], v[98:113]
	v_mfma_f32_32x32x16_bf16 v[82:97], v[198:201], v[240:243], v[82:97]
	v_mfma_f32_32x32x16_bf16 v[66:81], v[202:205], v[240:243], v[66:81]
	s_waitcnt lgkmcnt(1)
	v_mfma_f32_32x32x16_bf16 v[50:65], v[198:201], v[244:247], v[50:65]
	v_mfma_f32_32x32x16_bf16 v[34:49], v[202:205], v[244:247], v[34:49]
	s_waitcnt lgkmcnt(0)
	v_mfma_f32_32x32x16_bf16 v[18:33], v[198:201], v[206:209], v[18:33]
	v_mfma_f32_32x32x16_bf16 v[2:17], v[202:205], v[206:209], v[2:17]
	s_setprio 0
	s_cbranch_scc1 .Ltail_92
	s_add_i32 s21, s14, 1
	s_cmp_ge_i32 s21, s16
	s_cbranch_scc1 .Lx91_92
	s_bfe_u32 s22, s21, 0x20001
	s_bitcmp1_b32 s14, 0
	s_cselect_b64 s[4:5], -1, 0
	s_and_b64 vcc, exec, s[4:5]
	s_cbranch_vccnz .Lx89_92
	s_cmp_lt_i32 s22, 1
	s_mov_b64 s[4:5], 0xfc00000
	s_cbranch_scc1 .Lx88_92
	s_cmp_eq_u32 s22, 1
	s_mov_b64 s[8:9], -1
	s_cbranch_scc1 .Lx86_92
	s_cmp_eq_u32 s22, 2
	s_mov_b32 s4, 0x4c00000
	s_cselect_b32 s80, s4, 0x9c00000
	s_mov_b64 s[8:9], 0
	s_mov_b64 s[4:5], s[80:81]

.LcL_647:
	s_waitcnt lgkmcnt(0)
	s_barrier
	s_setprio 2
	ds_read_b128 v[178:181], v183 offset:36864
	ds_read_b128 v[194:197], v183 offset:41472
	ds_read_b128 v[206:209], v182
	ds_read_b128 v[216:219], v182 offset:4608
	ds_read_b128 v[236:239], v182 offset:9216
	ds_read_b128 v[240:243], v182 offset:13824
	ds_read_b128 v[244:247], v182 offset:32
	s_waitcnt lgkmcnt(4)
	v_mfma_f32_32x32x16_bf16 v[114:129], v[178:181], v[206:209], v[114:129]
	s_ashr_i32 s1, s0, 31
	s_lshl_b64 s[4:5], s[0:1], 7
	v_lshl_add_u64 v[154:155], v[184:185], 0, s[4:5]
	v_mfma_f32_32x32x16_bf16 v[50:65], v[194:197], v[206:209], v[50:65]
	global_load_dwordx4 v[142:145], v[154:155], off
	s_nop 0
	v_add_co_u32_e32 v130, vcc, 0x10000, v154
	ds_read_b128 v[206:209], v182 offset:4640
	ds_read_b128 v[198:201], v183 offset:36896
	ds_read_b128 v[202:205], v183 offset:41504
	s_waitcnt lgkmcnt(6)
	v_mfma_f32_32x32x16_bf16 v[98:113], v[178:181], v[216:219], v[98:113]
	v_addc_co_u32_e32 v131, vcc, 0, v155, vcc
	global_load_dwordx4 v[130:133], v[130:131], off
	v_add_co_u32_e32 v134, vcc, 0x20000, v154
	v_mfma_f32_32x32x16_bf16 v[34:49], v[194:197], v[216:219], v[34:49]
	v_addc_co_u32_e32 v135, vcc, 0, v155, vcc
	global_load_dwordx4 v[134:137], v[134:135], off
	s_nop 0
	ds_read_b128 v[216:219], v182 offset:9248
	s_waitcnt lgkmcnt(6)
	v_mfma_f32_32x32x16_bf16 v[82:97], v[178:181], v[236:239], v[82:97]
	v_add_co_u32_e32 v138, vcc, 0x30000, v154
	v_addc_co_u32_e32 v139, vcc, 0, v155, vcc
	global_load_dwordx4 v[138:141], v[138:139], off
	v_mfma_f32_32x32x16_bf16 v[18:33], v[194:197], v[236:239], v[18:33]
	v_add_co_u32_e32 v146, vcc, 0x40000, v154
	v_addc_co_u32_e32 v147, vcc, 0, v155, vcc
	global_load_dwordx4 v[146:149], v[146:147], off
	ds_read_b128 v[236:239], v182 offset:13856
	s_waitcnt lgkmcnt(6)
	v_mfma_f32_32x32x16_bf16 v[66:81], v[178:181], v[240:243], v[66:81]
	s_nop 0
	v_add_co_u32_e32 v150, vcc, 0x50000, v154
	s_nop 0
	v_mfma_f32_32x32x16_bf16 v[2:17], v[194:197], v[240:243], v[2:17]
	v_addc_co_u32_e32 v151, vcc, 0, v155, vcc
	global_load_dwordx4 v[150:153], v[150:151], off
	v_add_co_u32_e32 v156, vcc, 0x60000, v154
	ds_read_b128 v[240:243], v182 offset:64
	s_waitcnt lgkmcnt(3)
	v_mfma_f32_32x32x16_bf16 v[114:129], v[198:201], v[244:247], v[114:129]
	v_addc_co_u32_e32 v157, vcc, 0, v155, vcc
	v_add_co_u32_e32 v158, vcc, 0x70000, v154
	s_nop 1
	v_mfma_f32_32x32x16_bf16 v[50:65], v[202:205], v[244:247], v[50:65]
	v_addc_co_u32_e32 v159, vcc, 0, v155, vcc
	global_load_dwordx4 v[154:157], v[156:157], off
	s_nop 0
	ds_read_b128 v[244:247], v182 offset:4672
	ds_read_b128 v[178:181], v183 offset:36928
	ds_read_b128 v[194:197], v183 offset:41536
	v_mfma_f32_32x32x16_bf16 v[98:113], v[198:201], v[206:209], v[98:113]
	global_load_dwordx4 v[158:161], v[158:159], off
	v_lshl_add_u64 v[170:171], v[186:187], 0, s[4:5]
	s_nop 0
	v_mfma_f32_32x32x16_bf16 v[34:49], v[202:205], v[206:209], v[34:49]
	global_load_dwordx4 v[162:165], v[170:171], off
	s_nop 0
	v_add_co_u32_e32 v166, vcc, 0x10000, v170
	ds_read_b128 v[206:209], v182 offset:9280
	s_waitcnt lgkmcnt(6)
	v_mfma_f32_32x32x16_bf16 v[82:97], v[198:201], v[216:219], v[82:97]
	v_addc_co_u32_e32 v167, vcc, 0, v171, vcc
	global_load_dwordx4 v[166:169], v[166:167], off
	v_add_co_u32_e32 v172, vcc, 0x20000, v170
	v_mfma_f32_32x32x16_bf16 v[18:33], v[202:205], v[216:219], v[18:33]
	v_addc_co_u32_e32 v173, vcc, 0, v171, vcc
	v_add_co_u32_e32 v174, vcc, 0x30000, v170
	s_nop 1
	ds_read_b128 v[216:219], v182 offset:13888
	s_waitcnt lgkmcnt(6)
	v_mfma_f32_32x32x16_bf16 v[66:81], v[198:201], v[236:239], v[66:81]
	v_addc_co_u32_e32 v175, vcc, 0, v171, vcc
	global_load_dwordx4 v[170:173], v[172:173], off
	s_nop 0
	v_mfma_f32_32x32x16_bf16 v[2:17], v[202:205], v[236:239], v[2:17]
	global_load_dwordx4 v[174:177], v[174:175], off
	s_add_i32 s0, s0, 1
	s_nop 0
	ds_read_b128 v[236:239], v182 offset:96
	s_waitcnt lgkmcnt(3)
	v_mfma_f32_32x32x16_bf16 v[114:129], v[178:181], v[240:243], v[114:129]
	s_cmp_lg_u32 s0, 16
	v_mfma_f32_32x32x16_bf16 v[50:65], v[194:197], v[240:243], v[50:65]
	ds_read_b128 v[240:243], v182 offset:4704
	ds_read_b128 v[198:201], v183 offset:36960
	ds_read_b128 v[202:205], v183 offset:41568
	v_mfma_f32_32x32x16_bf16 v[98:113], v[178:181], v[244:247], v[98:113]
	v_mfma_f32_32x32x16_bf16 v[34:49], v[194:197], v[244:247], v[34:49]
	ds_read_b128 v[244:247], v182 offset:9312
	s_waitcnt lgkmcnt(6)
	v_mfma_f32_32x32x16_bf16 v[82:97], v[178:181], v[206:209], v[82:97]
	v_mfma_f32_32x32x16_bf16 v[18:33], v[194:197], v[206:209], v[18:33]
	ds_read_b128 v[206:209], v182 offset:13920
	s_waitcnt lgkmcnt(6)
	v_mfma_f32_32x32x16_bf16 v[66:81], v[178:181], v[216:219], v[66:81]
	v_mfma_f32_32x32x16_bf16 v[2:17], v[194:197], v[216:219], v[2:17]
	s_waitcnt lgkmcnt(2)
	v_mfma_f32_32x32x16_bf16 v[114:129], v[198:201], v[236:239], v[114:129]
	v_mfma_f32_32x32x16_bf16 v[50:65], v[202:205], v[236:239], v[50:65]
	v_mfma_f32_32x32x16_bf16 v[98:113], v[198:201], v[240:243], v[98:113]
	v_mfma_f32_32x32x16_bf16 v[34:49], v[202:205], v[240:243], v[34:49]
	s_waitcnt lgkmcnt(1)
	v_mfma_f32_32x32x16_bf16 v[82:97], v[198:201], v[244:247], v[82:97]
	v_mfma_f32_32x32x16_bf16 v[18:33], v[202:205], v[244:247], v[18:33]
	s_waitcnt lgkmcnt(0)
	v_mfma_f32_32x32x16_bf16 v[66:81], v[198:201], v[206:209], v[66:81]
	v_mfma_f32_32x32x16_bf16 v[2:17], v[202:205], v[206:209], v[2:17]
	s_setprio 0
	s_cbranch_scc1 .Ltail_647
	s_add_i32 s10, s10, 1
	s_cmp_ge_i32 s10, s8
	s_cbranch_scc1 .Lx646_647
	s_mul_i32 s0, s10, s82
	s_add_i32 s0, s0, s63
	s_ashr_i32 s1, s0, 31
	s_lshr_b32 s1, s1, 26
	s_add_i32 s1, s0, s1
	s_ashr_i32 s3, s1, 6
	s_andn2_b32 s1, s1, 63
	s_sub_i32 s0, s0, s1
	s_lshl_b32 s1, s3, 1
	s_and_b32 s3, s0, 1
	s_or_b32 s1, s3, s1
	v_readlane_b32 s4, v252, 35
	s_ashr_i32 s0, s0, 1
	s_sub_i32 s3, 0x7f, s1
	v_readlane_b32 s5, v252, 36
	s_and_b64 s[4:5], s[4:5], exec
	s_cselect_b32 s4, s3, s1
	s_ashr_i32 s5, s4, 31
	s_ashr_i32 s1, s0, 31
	s_lshl_b64 s[4:5], s[4:5], 19
	s_lshl_b64 s[0:1], s[0:1], 18
	v_lshl_add_u64 v[184:185], v[190:191], 0, s[4:5]
	v_lshl_add_u64 v[186:187], v[192:193], 0, s[0:1]

.LcL_801:
	s_waitcnt lgkmcnt(0)
	s_barrier
	s_setprio 2
	ds_read_b128 v[190:193], v179 offset:36864
	ds_read_b128 v[194:197], v179 offset:41472
	ds_read_b128 v[206:209], v178
	ds_read_b128 v[216:219], v178 offset:4608
	ds_read_b128 v[236:239], v178 offset:9216
	ds_read_b128 v[240:243], v178 offset:13824
	ds_read_b128 v[244:247], v178 offset:32
	s_waitcnt lgkmcnt(4)
	v_mfma_f32_32x32x16_bf16 v[98:113], v[190:193], v[206:209], v[98:113]
	s_ashr_i32 s3, s2, 31
	s_lshl_b64 s[10:11], s[2:3], 7
	v_lshl_add_u64 v[154:155], v[180:181], 0, s[10:11]
	v_mfma_f32_32x32x16_bf16 v[114:129], v[194:197], v[206:209], v[114:129]
	global_load_dwordx4 v[142:145], v[154:155], off
	s_nop 0
	v_add_co_u32_e32 v130, vcc, 0x2c000, v154
	ds_read_b128 v[206:209], v178 offset:4640
	ds_read_b128 v[198:201], v179 offset:36896
	ds_read_b128 v[202:205], v179 offset:41504
	s_waitcnt lgkmcnt(6)
	v_mfma_f32_32x32x16_bf16 v[82:97], v[190:193], v[216:219], v[82:97]
	v_addc_co_u32_e32 v131, vcc, 0, v155, vcc
	global_load_dwordx4 v[130:133], v[130:131], off
	v_add_co_u32_e32 v134, vcc, 0x58000, v154
	v_mfma_f32_32x32x16_bf16 v[66:81], v[194:197], v[216:219], v[66:81]
	v_addc_co_u32_e32 v135, vcc, 0, v155, vcc
	global_load_dwordx4 v[134:137], v[134:135], off
	s_nop 0
	ds_read_b128 v[216:219], v178 offset:9248
	s_waitcnt lgkmcnt(6)
	v_mfma_f32_32x32x16_bf16 v[50:65], v[190:193], v[236:239], v[50:65]
	v_add_co_u32_e32 v138, vcc, 0x84000, v154
	v_addc_co_u32_e32 v139, vcc, 0, v155, vcc
	global_load_dwordx4 v[138:141], v[138:139], off
	v_mfma_f32_32x32x16_bf16 v[34:49], v[194:197], v[236:239], v[34:49]
	v_add_co_u32_e32 v146, vcc, 0xb0000, v154
	v_addc_co_u32_e32 v147, vcc, 0, v155, vcc
	global_load_dwordx4 v[146:149], v[146:147], off
	ds_read_b128 v[236:239], v178 offset:13856
	s_waitcnt lgkmcnt(6)
	v_mfma_f32_32x32x16_bf16 v[18:33], v[190:193], v[240:243], v[18:33]
	s_nop 0
	v_add_co_u32_e32 v150, vcc, 0xdc000, v154
	s_nop 0
	v_mfma_f32_32x32x16_bf16 v[2:17], v[194:197], v[240:243], v[2:17]
	v_addc_co_u32_e32 v151, vcc, 0, v155, vcc
	global_load_dwordx4 v[150:153], v[150:151], off
	v_add_co_u32_e32 v156, vcc, 0x108000, v154
	ds_read_b128 v[240:243], v178 offset:64
	s_waitcnt lgkmcnt(3)
	v_mfma_f32_32x32x16_bf16 v[98:113], v[198:201], v[244:247], v[98:113]
	v_addc_co_u32_e32 v157, vcc, 0, v155, vcc
	v_add_co_u32_e32 v158, vcc, 0x134000, v154
	s_nop 1
	v_mfma_f32_32x32x16_bf16 v[114:129], v[202:205], v[244:247], v[114:129]
	v_addc_co_u32_e32 v159, vcc, 0, v155, vcc
	global_load_dwordx4 v[154:157], v[156:157], off
	s_nop 0
	ds_read_b128 v[244:247], v178 offset:4672
	ds_read_b128 v[190:193], v179 offset:36928
	ds_read_b128 v[194:197], v179 offset:41536
	v_mfma_f32_32x32x16_bf16 v[82:97], v[198:201], v[206:209], v[82:97]
	global_load_dwordx4 v[158:161], v[158:159], off
	v_lshl_add_u64 v[170:171], v[182:183], 0, s[10:11]
	s_nop 0
	v_mfma_f32_32x32x16_bf16 v[66:81], v[202:205], v[206:209], v[66:81]
	global_load_dwordx4 v[162:165], v[170:171], off
	s_nop 0
	v_add_co_u32_e32 v166, vcc, 0x2c000, v170
	ds_read_b128 v[206:209], v178 offset:9280
	s_waitcnt lgkmcnt(6)
	v_mfma_f32_32x32x16_bf16 v[50:65], v[198:201], v[216:219], v[50:65]
	v_addc_co_u32_e32 v167, vcc, 0, v171, vcc
	global_load_dwordx4 v[166:169], v[166:167], off
	v_add_co_u32_e32 v172, vcc, 0x58000, v170
	v_mfma_f32_32x32x16_bf16 v[34:49], v[202:205], v[216:219], v[34:49]
	v_addc_co_u32_e32 v173, vcc, 0, v171, vcc
	v_add_co_u32_e32 v174, vcc, 0x84000, v170
	s_nop 1
	ds_read_b128 v[216:219], v178 offset:13888
	s_waitcnt lgkmcnt(6)
	v_mfma_f32_32x32x16_bf16 v[18:33], v[198:201], v[236:239], v[18:33]
	v_addc_co_u32_e32 v175, vcc, 0, v171, vcc
	global_load_dwordx4 v[170:173], v[172:173], off
	s_nop 0
	v_mfma_f32_32x32x16_bf16 v[2:17], v[202:205], v[236:239], v[2:17]
	global_load_dwordx4 v[174:177], v[174:175], off
	s_add_i32 s2, s2, 1
	s_nop 0
	ds_read_b128 v[236:239], v178 offset:96
	s_waitcnt lgkmcnt(3)
	v_mfma_f32_32x32x16_bf16 v[98:113], v[190:193], v[240:243], v[98:113]
	s_cmp_lg_u32 s2, 44
	v_mfma_f32_32x32x16_bf16 v[114:129], v[194:197], v[240:243], v[114:129]
	ds_read_b128 v[240:243], v178 offset:4704
	ds_read_b128 v[198:201], v179 offset:36960
	ds_read_b128 v[202:205], v179 offset:41568
	v_mfma_f32_32x32x16_bf16 v[82:97], v[190:193], v[244:247], v[82:97]
	v_mfma_f32_32x32x16_bf16 v[66:81], v[194:197], v[244:247], v[66:81]
	ds_read_b128 v[244:247], v178 offset:9312
	s_waitcnt lgkmcnt(6)
	v_mfma_f32_32x32x16_bf16 v[50:65], v[190:193], v[206:209], v[50:65]
	v_mfma_f32_32x32x16_bf16 v[34:49], v[194:197], v[206:209], v[34:49]
	ds_read_b128 v[206:209], v178 offset:13920
	s_waitcnt lgkmcnt(6)
	v_mfma_f32_32x32x16_bf16 v[18:33], v[190:193], v[216:219], v[18:33]
	v_mfma_f32_32x32x16_bf16 v[2:17], v[194:197], v[216:219], v[2:17]
	s_waitcnt lgkmcnt(2)
	v_mfma_f32_32x32x16_bf16 v[98:113], v[198:201], v[236:239], v[98:113]
	v_mfma_f32_32x32x16_bf16 v[114:129], v[202:205], v[236:239], v[114:129]
	v_mfma_f32_32x32x16_bf16 v[82:97], v[198:201], v[240:243], v[82:97]
	v_mfma_f32_32x32x16_bf16 v[66:81], v[202:205], v[240:243], v[66:81]
	s_waitcnt lgkmcnt(1)
	v_mfma_f32_32x32x16_bf16 v[50:65], v[198:201], v[244:247], v[50:65]
	v_mfma_f32_32x32x16_bf16 v[34:49], v[202:205], v[244:247], v[34:49]
	s_waitcnt lgkmcnt(0)
	v_mfma_f32_32x32x16_bf16 v[18:33], v[198:201], v[206:209], v[18:33]
	v_mfma_f32_32x32x16_bf16 v[2:17], v[202:205], v[206:209], v[2:17]
	s_setprio 0
	s_cbranch_scc1 .Ltail_801
	s_add_i32 s4, s4, 1
	s_cmp_ge_i32 s4, s8
	s_cbranch_scc1 .Lz_801
	s_mul_i32 s2, s4, s82
	s_add_i32 s2, s2, s63
	s_ashr_i32 s3, s2, 31
	s_lshr_b32 s3, s3, 28
	s_add_i32 s3, s2, s3
	s_ashr_i32 s10, s3, 4
	s_and_b32 s3, s3, -16
	s_sub_i32 s2, s2, s3
	s_lshl_b32 s3, s10, 1
	s_and_b32 s10, s2, 1
	s_or_b32 s10, s10, s3
	s_lshr_b32 s11, s2, 1
	v_readlane_b32 s2, v252, 35
	s_sub_i32 s12, 0x7f, s10
	v_readlane_b32 s3, v252, 36
	s_and_b64 s[2:3], s[2:3], exec
	s_mul_i32 s2, s11, 0x58000
	s_cselect_b32 s10, s12, s10
	s_ashr_i32 s3, s2, 31
	v_mov_b32_e32 v0, 0x160000
	v_mad_i64_i32 v[180:181], s[10:11], s10, v0, v[186:187]
	v_lshl_add_u64 v[182:183], s[2:3], 1, v[188:189]

.LcL_815:
	s_waitcnt lgkmcnt(0)
	s_barrier
	s_setprio 2
	ds_read_b128 v[190:193], v179 offset:36864
	ds_read_b128 v[194:197], v179 offset:41472
	ds_read_b128 v[206:209], v178
	ds_read_b128 v[216:219], v178 offset:4608
	ds_read_b128 v[236:239], v178 offset:9216
	ds_read_b128 v[240:243], v178 offset:13824
	ds_read_b128 v[244:247], v178 offset:32
	s_waitcnt lgkmcnt(4)
	v_mfma_f32_32x32x16_bf16 v[114:129], v[190:193], v[206:209], v[114:129]
	s_ashr_i32 s1, s0, 31
	s_lshl_b64 s[8:9], s[0:1], 7
	v_lshl_add_u64 v[154:155], v[180:181], 0, s[8:9]
	v_mfma_f32_32x32x16_bf16 v[98:113], v[194:197], v[206:209], v[98:113]
	global_load_dwordx4 v[142:145], v[154:155], off
	s_nop 0
	v_add_co_u32_e32 v130, vcc, 0x10000, v154
	ds_read_b128 v[206:209], v178 offset:4640
	ds_read_b128 v[198:201], v179 offset:36896
	ds_read_b128 v[202:205], v179 offset:41504
	s_waitcnt lgkmcnt(6)
	v_mfma_f32_32x32x16_bf16 v[82:97], v[190:193], v[216:219], v[82:97]
	v_addc_co_u32_e32 v131, vcc, 0, v155, vcc
	global_load_dwordx4 v[130:133], v[130:131], off
	v_add_co_u32_e32 v134, vcc, 0x20000, v154
	v_mfma_f32_32x32x16_bf16 v[66:81], v[194:197], v[216:219], v[66:81]
	v_addc_co_u32_e32 v135, vcc, 0, v155, vcc
	global_load_dwordx4 v[134:137], v[134:135], off
	s_nop 0
	ds_read_b128 v[216:219], v178 offset:9248
	s_waitcnt lgkmcnt(6)
	v_mfma_f32_32x32x16_bf16 v[50:65], v[190:193], v[236:239], v[50:65]
	v_add_co_u32_e32 v138, vcc, 0x30000, v154
	v_addc_co_u32_e32 v139, vcc, 0, v155, vcc
	global_load_dwordx4 v[138:141], v[138:139], off
	v_mfma_f32_32x32x16_bf16 v[34:49], v[194:197], v[236:239], v[34:49]
	v_add_co_u32_e32 v146, vcc, 0x40000, v154
	v_addc_co_u32_e32 v147, vcc, 0, v155, vcc
	global_load_dwordx4 v[146:149], v[146:147], off
	ds_read_b128 v[236:239], v178 offset:13856
	s_waitcnt lgkmcnt(6)
	v_mfma_f32_32x32x16_bf16 v[18:33], v[190:193], v[240:243], v[18:33]
	s_nop 0
	v_add_co_u32_e32 v150, vcc, 0x50000, v154
	s_nop 0
	v_mfma_f32_32x32x16_bf16 v[2:17], v[194:197], v[240:243], v[2:17]
	v_addc_co_u32_e32 v151, vcc, 0, v155, vcc
	global_load_dwordx4 v[150:153], v[150:151], off
	v_add_co_u32_e32 v156, vcc, 0x60000, v154
	ds_read_b128 v[240:243], v178 offset:64
	s_waitcnt lgkmcnt(3)
	v_mfma_f32_32x32x16_bf16 v[114:129], v[198:201], v[244:247], v[114:129]
	v_addc_co_u32_e32 v157, vcc, 0, v155, vcc
	v_add_co_u32_e32 v158, vcc, 0x70000, v154
	s_nop 1
	v_mfma_f32_32x32x16_bf16 v[98:113], v[202:205], v[244:247], v[98:113]
	v_addc_co_u32_e32 v159, vcc, 0, v155, vcc
	global_load_dwordx4 v[154:157], v[156:157], off
	s_nop 0
	ds_read_b128 v[244:247], v178 offset:4672
	ds_read_b128 v[190:193], v179 offset:36928
	ds_read_b128 v[194:197], v179 offset:41536
	v_mfma_f32_32x32x16_bf16 v[82:97], v[198:201], v[206:209], v[82:97]
	global_load_dwordx4 v[158:161], v[158:159], off
	v_lshl_add_u64 v[170:171], v[182:183], 0, s[8:9]
	s_nop 0
	v_mfma_f32_32x32x16_bf16 v[66:81], v[202:205], v[206:209], v[66:81]
	global_load_dwordx4 v[162:165], v[170:171], off
	s_nop 0
	v_add_co_u32_e32 v166, vcc, 0x10000, v170
	ds_read_b128 v[206:209], v178 offset:9280
	s_waitcnt lgkmcnt(6)
	v_mfma_f32_32x32x16_bf16 v[50:65], v[198:201], v[216:219], v[50:65]
	v_addc_co_u32_e32 v167, vcc, 0, v171, vcc
	global_load_dwordx4 v[166:169], v[166:167], off
	v_add_co_u32_e32 v172, vcc, 0x20000, v170
	v_mfma_f32_32x32x16_bf16 v[34:49], v[202:205], v[216:219], v[34:49]
	v_addc_co_u32_e32 v173, vcc, 0, v171, vcc
	v_add_co_u32_e32 v174, vcc, 0x30000, v170
	s_nop 1
	ds_read_b128 v[216:219], v178 offset:13888
	s_waitcnt lgkmcnt(6)
	v_mfma_f32_32x32x16_bf16 v[18:33], v[198:201], v[236:239], v[18:33]
	v_addc_co_u32_e32 v175, vcc, 0, v171, vcc
	global_load_dwordx4 v[170:173], v[172:173], off
	s_nop 0
	v_mfma_f32_32x32x16_bf16 v[2:17], v[202:205], v[236:239], v[2:17]
	global_load_dwordx4 v[174:177], v[174:175], off
	s_add_i32 s0, s0, 1
	s_nop 0
	ds_read_b128 v[236:239], v178 offset:96
	s_waitcnt lgkmcnt(3)
	v_mfma_f32_32x32x16_bf16 v[114:129], v[190:193], v[240:243], v[114:129]
	s_cmp_lg_u32 s0, 16
	v_mfma_f32_32x32x16_bf16 v[98:113], v[194:197], v[240:243], v[98:113]
	ds_read_b128 v[240:243], v178 offset:4704
	ds_read_b128 v[198:201], v179 offset:36960
	ds_read_b128 v[202:205], v179 offset:41568
	v_mfma_f32_32x32x16_bf16 v[82:97], v[190:193], v[244:247], v[82:97]
	v_mfma_f32_32x32x16_bf16 v[66:81], v[194:197], v[244:247], v[66:81]
	ds_read_b128 v[244:247], v178 offset:9312
	s_waitcnt lgkmcnt(6)
	v_mfma_f32_32x32x16_bf16 v[50:65], v[190:193], v[206:209], v[50:65]
	v_mfma_f32_32x32x16_bf16 v[34:49], v[194:197], v[206:209], v[34:49]
	ds_read_b128 v[206:209], v178 offset:13920
	s_waitcnt lgkmcnt(6)
	v_mfma_f32_32x32x16_bf16 v[18:33], v[190:193], v[216:219], v[18:33]
	v_mfma_f32_32x32x16_bf16 v[2:17], v[194:197], v[216:219], v[2:17]
	s_waitcnt lgkmcnt(2)
	v_mfma_f32_32x32x16_bf16 v[114:129], v[198:201], v[236:239], v[114:129]
	v_mfma_f32_32x32x16_bf16 v[98:113], v[202:205], v[236:239], v[98:113]
	v_mfma_f32_32x32x16_bf16 v[82:97], v[198:201], v[240:243], v[82:97]
	v_mfma_f32_32x32x16_bf16 v[66:81], v[202:205], v[240:243], v[66:81]
	s_waitcnt lgkmcnt(1)
	v_mfma_f32_32x32x16_bf16 v[50:65], v[198:201], v[244:247], v[50:65]
	v_mfma_f32_32x32x16_bf16 v[34:49], v[202:205], v[244:247], v[34:49]
	s_waitcnt lgkmcnt(0)
	v_mfma_f32_32x32x16_bf16 v[18:33], v[198:201], v[206:209], v[18:33]
	v_mfma_f32_32x32x16_bf16 v[2:17], v[202:205], v[206:209], v[2:17]
	s_setprio 0
	s_cbranch_scc1 .Ltail_815
	s_add_i32 s2, s2, 1
	s_cmp_ge_i32 s2, s4
	s_cbranch_scc1 .Lz_815
	s_mul_i32 s0, s2, s82
	s_add_i32 s0, s0, s63
	s_mul_hi_i32 s1, s0, 0x2e8ba2e9
	s_lshr_b32 s8, s1, 31
	s_ashr_i32 s1, s1, 4
	s_add_i32 s1, s1, s8
	s_mul_i32 s8, s1, 0x58
	s_sub_i32 s0, s0, s8
	s_lshl_b32 s1, s1, 1
	s_and_b32 s8, s0, 1
	s_or_b32 s1, s8, s1
	v_readlane_b32 s8, v252, 35
	s_ashr_i32 s0, s0, 1
	s_sub_i32 s10, 0x7f, s1
	v_readlane_b32 s9, v252, 36
	s_and_b64 s[8:9], s[8:9], exec
	s_cselect_b32 s8, s10, s1
	s_ashr_i32 s9, s8, 31
	s_ashr_i32 s1, s0, 31
	s_lshl_b64 s[8:9], s[8:9], 19
	s_lshl_b64 s[0:1], s[0:1], 18
	v_lshl_add_u64 v[180:181], v[186:187], 0, s[8:9]
	v_lshl_add_u64 v[182:183], v[188:189], 0, s[0:1]
